# layer-0 w_in GEMM main tiles: XCDs 7 decode positions apart
# speedup vs baseline: 1.0047x; 1.0047x over previous
.Lgi_sk_rot0:
	s_and_b32 s0, s54, 7
	s_lshr_b32 s1, s54, 3
	s_mul_i32 s57, s0, 187
	s_add_u32 s1, s1, s57
	s_mul_i32 s57, s1, 0x5556
	s_lshr_b32 s57, s57, 22
	s_mul_i32 s57, s57, 192
	s_sub_u32 s1, s1, s57
	s_lshl_b32 s1, s1, 3
	s_or_b32 s57, s1, s0
	s_branch .Lgi_sk_dec
